# t1 + attention unit epilogues: all 16 gate loads issued up front into dead softmax registers, per-step counted waits
# baseline (speedup 1.0000x reference)
.LBB0_517:
	v_lshlrev_b64 v[4:5], 12, v[176:177]
	v_lshl_add_u64 v[2:3], v[172:173], 0, v[4:5]
	global_load_dwordx2 v[6:7], v[2:3], off
	global_load_dwordx2 v[8:9], v[2:3], off offset:16
	global_load_dwordx2 v[80:81], v[2:3], off offset:32
	global_load_dwordx2 v[82:83], v[2:3], off offset:48
	global_load_dwordx2 v[84:85], v[2:3], off offset:64
	global_load_dwordx2 v[86:87], v[2:3], off offset:80
	global_load_dwordx2 v[88:89], v[2:3], off offset:96
	global_load_dwordx2 v[90:91], v[2:3], off offset:112
	global_load_dwordx2 v[92:93], v[2:3], off offset:128
	global_load_dwordx2 v[94:95], v[2:3], off offset:144
	global_load_dwordx2 v[96:97], v[2:3], off offset:160
	global_load_dwordx2 v[98:99], v[2:3], off offset:176
	global_load_dwordx2 v[100:101], v[2:3], off offset:192
	global_load_dwordx2 v[102:103], v[2:3], off offset:208
	global_load_dwordx2 v[104:105], v[2:3], off offset:224
	global_load_dwordx2 v[106:107], v[2:3], off offset:240
	v_rcp_f32_e32 v0, v163
	v_lshl_add_u64 v[4:5], v[170:171], 0, v[4:5]
	s_mov_b64 s[78:79], 0
	s_and_b64 vcc, exec, s[4:5]
	v_mul_f32_e32 v10, v0, v64
	v_mul_f32_e32 v11, v0, v65
	v_mul_f32_e32 v12, v0, v66
	v_mul_f32_e32 v13, v0, v67
	v_mul_f32_e32 v14, v0, v68
	v_mul_f32_e32 v15, v0, v69
	v_mul_f32_e32 v64, v0, v70
	v_mul_f32_e32 v65, v0, v71
	s_waitcnt vmcnt(14)
	v_lshlrev_b32_e32 v66, 16, v6
	v_and_b32_e32 v6, 0xffff0000, v6
	v_lshlrev_b32_e32 v67, 16, v7
	v_and_b32_e32 v7, 0xffff0000, v7
	v_lshlrev_b32_e32 v68, 16, v8
	v_and_b32_e32 v8, 0xffff0000, v8
	v_lshlrev_b32_e32 v69, 16, v9
	v_and_b32_e32 v9, 0xffff0000, v9
	v_mul_f32_e32 v10, v10, v66
	v_mul_f32_e32 v6, v11, v6
	v_mul_f32_e32 v11, v12, v67
	v_mul_f32_e32 v7, v13, v7
	v_mul_f32_e32 v12, v14, v68
	v_mul_f32_e32 v8, v15, v8
	v_mul_f32_e32 v13, v64, v69
	v_mul_f32_e32 v9, v65, v9
	v_cvt_pk_bf16_f32 v6, v10, v6
	v_cvt_pk_bf16_f32 v7, v11, v7
	v_cvt_pk_bf16_f32 v8, v12, v8
	v_cvt_pk_bf16_f32 v9, v13, v9
	v_permlane32_swap_b32_e32 v6, v8
	v_permlane32_swap_b32_e32 v7, v9
	v_mul_f32_e32 v14, v0, v72
	v_mul_f32_e32 v15, v0, v73
	v_mul_f32_e32 v64, v0, v74
	v_mul_f32_e32 v65, v0, v75
	v_mul_f32_e32 v66, v0, v76
	v_mul_f32_e32 v67, v0, v77
	v_mul_f32_e32 v68, v0, v78
	v_mul_f32_e32 v69, v0, v79
	global_store_dwordx4 v[4:5], v[6:9], off
	s_waitcnt vmcnt(13)
	v_mov_b32_e32 v10, v80
	v_mov_b32_e32 v11, v81
	v_mov_b32_e32 v12, v82
	v_mov_b32_e32 v13, v83
	s_nop 0
	v_lshlrev_b32_e32 v6, 16, v10
	v_and_b32_e32 v7, 0xffff0000, v10
	v_lshlrev_b32_e32 v8, 16, v11
	v_and_b32_e32 v9, 0xffff0000, v11
	v_lshlrev_b32_e32 v10, 16, v12
	v_and_b32_e32 v11, 0xffff0000, v12
	v_lshlrev_b32_e32 v12, 16, v13
	v_and_b32_e32 v13, 0xffff0000, v13
	v_mul_f32_e32 v6, v14, v6
	v_mul_f32_e32 v7, v15, v7
	v_mul_f32_e32 v8, v64, v8
	v_mul_f32_e32 v9, v65, v9
	v_mul_f32_e32 v10, v66, v10
	v_mul_f32_e32 v11, v67, v11
	v_mul_f32_e32 v12, v68, v12
	v_mul_f32_e32 v13, v69, v13
	v_cvt_pk_bf16_f32 v6, v6, v7
	v_cvt_pk_bf16_f32 v7, v8, v9
	v_cvt_pk_bf16_f32 v8, v10, v11
	v_cvt_pk_bf16_f32 v9, v12, v13
	v_permlane32_swap_b32_e32 v6, v8
	v_permlane32_swap_b32_e32 v7, v9
	v_mul_f32_e32 v14, v0, v48
	v_mul_f32_e32 v15, v0, v49
	v_mul_f32_e32 v48, v0, v50
	v_mul_f32_e32 v49, v0, v51
	v_mul_f32_e32 v50, v0, v52
	v_mul_f32_e32 v51, v0, v53
	v_mul_f32_e32 v52, v0, v54
	v_mul_f32_e32 v53, v0, v55
	global_store_dwordx4 v[4:5], v[6:9], off offset:32
	s_waitcnt vmcnt(12)
	v_mov_b32_e32 v10, v84
	v_mov_b32_e32 v11, v85
	v_mov_b32_e32 v12, v86
	v_mov_b32_e32 v13, v87
	s_nop 0
	v_lshlrev_b32_e32 v6, 16, v10
	v_and_b32_e32 v7, 0xffff0000, v10
	v_lshlrev_b32_e32 v8, 16, v11
	v_and_b32_e32 v9, 0xffff0000, v11
	v_lshlrev_b32_e32 v10, 16, v12
	v_and_b32_e32 v11, 0xffff0000, v12
	v_lshlrev_b32_e32 v12, 16, v13
	v_and_b32_e32 v13, 0xffff0000, v13
	v_mul_f32_e32 v6, v14, v6
	v_mul_f32_e32 v7, v15, v7
	v_mul_f32_e32 v8, v48, v8
	v_mul_f32_e32 v9, v49, v9
	v_mul_f32_e32 v10, v50, v10
	v_mul_f32_e32 v11, v51, v11
	v_mul_f32_e32 v12, v52, v12
	v_mul_f32_e32 v13, v53, v13
	v_cvt_pk_bf16_f32 v6, v6, v7
	v_cvt_pk_bf16_f32 v7, v8, v9
	v_cvt_pk_bf16_f32 v8, v10, v11
	v_cvt_pk_bf16_f32 v9, v12, v13
	v_permlane32_swap_b32_e32 v6, v8
	v_permlane32_swap_b32_e32 v7, v9
	v_mul_f32_e32 v14, v0, v56
	v_mul_f32_e32 v15, v0, v57
	v_mul_f32_e32 v48, v0, v58
	v_mul_f32_e32 v49, v0, v59
	v_mul_f32_e32 v50, v0, v60
	v_mul_f32_e32 v51, v0, v61
	v_mul_f32_e32 v52, v0, v62
	v_mul_f32_e32 v53, v0, v63
	global_store_dwordx4 v[4:5], v[6:9], off offset:64
	s_waitcnt vmcnt(11)
	v_mov_b32_e32 v10, v88
	v_mov_b32_e32 v11, v89
	v_mov_b32_e32 v12, v90
	v_mov_b32_e32 v13, v91
	s_nop 0
	v_lshlrev_b32_e32 v6, 16, v10
	v_and_b32_e32 v7, 0xffff0000, v10
	v_lshlrev_b32_e32 v8, 16, v11
	v_and_b32_e32 v9, 0xffff0000, v11
	v_lshlrev_b32_e32 v10, 16, v12
	v_and_b32_e32 v11, 0xffff0000, v12
	v_lshlrev_b32_e32 v12, 16, v13
	v_and_b32_e32 v13, 0xffff0000, v13
	v_mul_f32_e32 v6, v14, v6
	v_mul_f32_e32 v7, v15, v7
	v_mul_f32_e32 v8, v48, v8
	v_mul_f32_e32 v9, v49, v9
	v_mul_f32_e32 v10, v50, v10
	v_mul_f32_e32 v11, v51, v11
	v_mul_f32_e32 v12, v52, v12
	v_mul_f32_e32 v13, v53, v13
	v_cvt_pk_bf16_f32 v6, v6, v7
	v_cvt_pk_bf16_f32 v7, v8, v9
	v_cvt_pk_bf16_f32 v8, v10, v11
	v_cvt_pk_bf16_f32 v9, v12, v13
	v_permlane32_swap_b32_e32 v6, v8
	v_permlane32_swap_b32_e32 v7, v9
	v_mul_f32_e32 v14, v0, v32
	v_mul_f32_e32 v15, v0, v33
	v_mul_f32_e32 v32, v0, v34
	v_mul_f32_e32 v33, v0, v35
	v_mul_f32_e32 v34, v0, v36
	v_mul_f32_e32 v35, v0, v37
	v_mul_f32_e32 v36, v0, v38
	v_mul_f32_e32 v37, v0, v39
	global_store_dwordx4 v[4:5], v[6:9], off offset:96
	s_waitcnt vmcnt(10)
	v_mov_b32_e32 v10, v92
	v_mov_b32_e32 v11, v93
	v_mov_b32_e32 v12, v94
	v_mov_b32_e32 v13, v95
	s_nop 0
	v_lshlrev_b32_e32 v6, 16, v10
	v_and_b32_e32 v7, 0xffff0000, v10
	v_lshlrev_b32_e32 v8, 16, v11
	v_and_b32_e32 v9, 0xffff0000, v11
	v_lshlrev_b32_e32 v10, 16, v12
	v_and_b32_e32 v11, 0xffff0000, v12
	v_lshlrev_b32_e32 v12, 16, v13
	v_and_b32_e32 v13, 0xffff0000, v13
	v_mul_f32_e32 v6, v14, v6
	v_mul_f32_e32 v7, v15, v7
	v_mul_f32_e32 v8, v32, v8
	v_mul_f32_e32 v9, v33, v9
	v_mul_f32_e32 v10, v34, v10
	v_mul_f32_e32 v11, v35, v11
	v_mul_f32_e32 v12, v36, v12
	v_mul_f32_e32 v13, v37, v13
	v_cvt_pk_bf16_f32 v6, v6, v7
	v_cvt_pk_bf16_f32 v7, v8, v9
	v_cvt_pk_bf16_f32 v8, v10, v11
	v_cvt_pk_bf16_f32 v9, v12, v13
	v_permlane32_swap_b32_e32 v6, v8
	v_permlane32_swap_b32_e32 v7, v9
	v_mul_f32_e32 v14, v0, v40
	v_mul_f32_e32 v15, v0, v41
	v_mul_f32_e32 v32, v0, v42
	v_mul_f32_e32 v33, v0, v43
	v_mul_f32_e32 v34, v0, v44
	v_mul_f32_e32 v35, v0, v45
	v_mul_f32_e32 v36, v0, v46
	v_mul_f32_e32 v37, v0, v47
	global_store_dwordx4 v[4:5], v[6:9], off offset:128
	s_waitcnt vmcnt(9)
	v_mov_b32_e32 v10, v96
	v_mov_b32_e32 v11, v97
	v_mov_b32_e32 v12, v98
	v_mov_b32_e32 v13, v99
	s_nop 0
	v_lshlrev_b32_e32 v6, 16, v10
	v_and_b32_e32 v7, 0xffff0000, v10
	v_lshlrev_b32_e32 v8, 16, v11
	v_and_b32_e32 v9, 0xffff0000, v11
	v_lshlrev_b32_e32 v10, 16, v12
	v_and_b32_e32 v11, 0xffff0000, v12
	v_lshlrev_b32_e32 v12, 16, v13
	v_and_b32_e32 v13, 0xffff0000, v13
	v_mul_f32_e32 v6, v14, v6
	v_mul_f32_e32 v7, v15, v7
	v_mul_f32_e32 v8, v32, v8
	v_mul_f32_e32 v9, v33, v9
	v_mul_f32_e32 v10, v34, v10
	v_mul_f32_e32 v11, v35, v11
	v_mul_f32_e32 v12, v36, v12
	v_mul_f32_e32 v13, v37, v13
	v_cvt_pk_bf16_f32 v6, v6, v7
	v_cvt_pk_bf16_f32 v7, v8, v9
	v_cvt_pk_bf16_f32 v8, v10, v11
	v_cvt_pk_bf16_f32 v9, v12, v13
	v_permlane32_swap_b32_e32 v6, v8
	v_permlane32_swap_b32_e32 v7, v9
	v_mul_f32_e32 v14, v0, v16
	v_mul_f32_e32 v15, v0, v17
	v_mul_f32_e32 v16, v0, v18
	v_mul_f32_e32 v17, v0, v19
	v_mul_f32_e32 v18, v0, v20
	v_mul_f32_e32 v19, v0, v21
	global_store_dwordx4 v[4:5], v[6:9], off offset:160
	v_mul_f32_e32 v20, v0, v22
	v_mul_f32_e32 v21, v0, v23
	s_waitcnt vmcnt(8)
	v_mov_b32_e32 v10, v100
	v_mov_b32_e32 v11, v101
	v_mov_b32_e32 v12, v102
	v_mov_b32_e32 v13, v103
	v_lshlrev_b32_e32 v6, 16, v10
	v_and_b32_e32 v7, 0xffff0000, v10
	v_lshlrev_b32_e32 v8, 16, v11
	v_and_b32_e32 v9, 0xffff0000, v11
	v_lshlrev_b32_e32 v10, 16, v12
	v_and_b32_e32 v11, 0xffff0000, v12
	v_lshlrev_b32_e32 v12, 16, v13
	v_and_b32_e32 v13, 0xffff0000, v13
	v_mul_f32_e32 v6, v14, v6
	v_mul_f32_e32 v7, v15, v7
	v_mul_f32_e32 v8, v16, v8
	v_mul_f32_e32 v9, v17, v9
	v_mul_f32_e32 v10, v18, v10
	v_mul_f32_e32 v11, v19, v11
	v_mul_f32_e32 v12, v20, v12
	v_mul_f32_e32 v13, v21, v13
	v_cvt_pk_bf16_f32 v6, v6, v7
	v_cvt_pk_bf16_f32 v7, v8, v9
	v_cvt_pk_bf16_f32 v8, v10, v11
	v_cvt_pk_bf16_f32 v9, v12, v13
	s_nop 0
	v_permlane32_swap_b32_e32 v6, v8
	v_permlane32_swap_b32_e32 v7, v9
	v_mul_f32_e32 v12, v0, v24
	v_mul_f32_e32 v13, v0, v25
	v_mul_f32_e32 v14, v0, v26
	v_mul_f32_e32 v15, v0, v27
	global_store_dwordx4 v[4:5], v[6:9], off offset:192
	v_mul_f32_e32 v16, v0, v28
	v_mul_f32_e32 v17, v0, v29
	v_mul_f32_e32 v18, v0, v30
	v_mul_f32_e32 v0, v0, v31
	s_waitcnt vmcnt(7)
	v_mov_b32_e32 v10, v104
	v_mov_b32_e32 v11, v105
	v_mov_b32_e32 v2, v106
	v_mov_b32_e32 v3, v107
	v_lshlrev_b32_e32 v6, 16, v10
	v_and_b32_e32 v7, 0xffff0000, v10
	v_lshlrev_b32_e32 v8, 16, v11
	v_and_b32_e32 v9, 0xffff0000, v11
	v_lshlrev_b32_e32 v10, 16, v2
	v_and_b32_e32 v2, 0xffff0000, v2
	v_lshlrev_b32_e32 v11, 16, v3
	v_and_b32_e32 v3, 0xffff0000, v3
	v_mul_f32_e32 v6, v12, v6
	v_mul_f32_e32 v7, v13, v7
	v_mul_f32_e32 v8, v14, v8
	v_mul_f32_e32 v9, v15, v9
	v_mul_f32_e32 v10, v16, v10
	v_mul_f32_e32 v2, v17, v2
	v_mul_f32_e32 v11, v18, v11
	v_mul_f32_e32 v0, v0, v3
	v_cvt_pk_bf16_f32 v6, v6, v7
	v_cvt_pk_bf16_f32 v7, v8, v9
	v_cvt_pk_bf16_f32 v8, v10, v2
	v_cvt_pk_bf16_f32 v9, v11, v0
	s_nop 0
	v_permlane32_swap_b32_e32 v6, v8
	v_permlane32_swap_b32_e32 v7, v9
	global_store_dwordx4 v[4:5], v[6:9], off offset:224
	s_waitcnt vmcnt(0) lgkmcnt(0)
	s_barrier
	s_cbranch_vccnz .LBB0_559

.LBB0_560:
	v_lshlrev_b64 v[4:5], 1, v[150:151]
	v_lshl_add_u64 v[2:3], v[172:173], 0, v[4:5]
	global_load_dwordx2 v[6:7], v[2:3], off offset:2048
	global_load_dwordx2 v[8:9], v[2:3], off offset:2064
	global_load_dwordx2 v[80:81], v[2:3], off offset:2080
	global_load_dwordx2 v[82:83], v[2:3], off offset:2096
	global_load_dwordx2 v[84:85], v[2:3], off offset:2112
	global_load_dwordx2 v[86:87], v[2:3], off offset:2128
	global_load_dwordx2 v[88:89], v[2:3], off offset:2144
	global_load_dwordx2 v[90:91], v[2:3], off offset:2160
	global_load_dwordx2 v[92:93], v[2:3], off offset:2176
	global_load_dwordx2 v[94:95], v[2:3], off offset:2192
	global_load_dwordx2 v[96:97], v[2:3], off offset:2208
	global_load_dwordx2 v[98:99], v[2:3], off offset:2224
	global_load_dwordx2 v[100:101], v[2:3], off offset:2240
	global_load_dwordx2 v[102:103], v[2:3], off offset:2256
	global_load_dwordx2 v[104:105], v[2:3], off offset:2272
	global_load_dwordx2 v[106:107], v[2:3], off offset:2288
	v_rcp_f32_e32 v0, v154
	v_lshl_add_u64 v[4:5], v[170:171], 0, v[4:5]
	s_mov_b64 s[84:85], 0
	s_and_b64 vcc, exec, s[4:5]
	v_mul_f32_e32 v10, v0, v64
	v_mul_f32_e32 v11, v0, v65
	v_mul_f32_e32 v12, v0, v66
	v_mul_f32_e32 v13, v0, v67
	v_mul_f32_e32 v14, v0, v68
	v_mul_f32_e32 v15, v0, v69
	v_mul_f32_e32 v64, v0, v70
	v_mul_f32_e32 v65, v0, v71
	s_waitcnt vmcnt(14)
	v_lshlrev_b32_e32 v66, 16, v6
	v_and_b32_e32 v6, 0xffff0000, v6
	v_lshlrev_b32_e32 v67, 16, v7
	v_and_b32_e32 v7, 0xffff0000, v7
	v_lshlrev_b32_e32 v68, 16, v8
	v_and_b32_e32 v8, 0xffff0000, v8
	v_lshlrev_b32_e32 v69, 16, v9
	v_and_b32_e32 v9, 0xffff0000, v9
	v_mul_f32_e32 v10, v10, v66
	v_mul_f32_e32 v6, v11, v6
	v_mul_f32_e32 v11, v12, v67
	v_mul_f32_e32 v7, v13, v7
	v_mul_f32_e32 v12, v14, v68
	v_mul_f32_e32 v8, v15, v8
	v_mul_f32_e32 v13, v64, v69
	v_mul_f32_e32 v9, v65, v9
	v_cvt_pk_bf16_f32 v6, v10, v6
	v_cvt_pk_bf16_f32 v7, v11, v7
	v_cvt_pk_bf16_f32 v8, v12, v8
	v_cvt_pk_bf16_f32 v9, v13, v9
	v_permlane32_swap_b32_e32 v6, v8
	v_permlane32_swap_b32_e32 v7, v9
	v_mul_f32_e32 v14, v0, v72
	v_mul_f32_e32 v15, v0, v73
	v_mul_f32_e32 v64, v0, v74
	v_mul_f32_e32 v65, v0, v75
	v_mul_f32_e32 v66, v0, v76
	v_mul_f32_e32 v67, v0, v77
	v_mul_f32_e32 v68, v0, v78
	v_mul_f32_e32 v69, v0, v79
	global_store_dwordx4 v[4:5], v[6:9], off offset:2048
	s_waitcnt vmcnt(13)
	v_mov_b32_e32 v10, v80
	v_mov_b32_e32 v11, v81
	v_mov_b32_e32 v12, v82
	v_mov_b32_e32 v13, v83
	s_nop 0
	v_lshlrev_b32_e32 v6, 16, v10
	v_and_b32_e32 v7, 0xffff0000, v10
	v_lshlrev_b32_e32 v8, 16, v11
	v_and_b32_e32 v9, 0xffff0000, v11
	v_lshlrev_b32_e32 v10, 16, v12
	v_and_b32_e32 v11, 0xffff0000, v12
	v_lshlrev_b32_e32 v12, 16, v13
	v_and_b32_e32 v13, 0xffff0000, v13
	v_mul_f32_e32 v6, v14, v6
	v_mul_f32_e32 v7, v15, v7
	v_mul_f32_e32 v8, v64, v8
	v_mul_f32_e32 v9, v65, v9
	v_mul_f32_e32 v10, v66, v10
	v_mul_f32_e32 v11, v67, v11
	v_mul_f32_e32 v12, v68, v12
	v_mul_f32_e32 v13, v69, v13
	v_cvt_pk_bf16_f32 v6, v6, v7
	v_cvt_pk_bf16_f32 v7, v8, v9
	v_cvt_pk_bf16_f32 v8, v10, v11
	v_cvt_pk_bf16_f32 v9, v12, v13
	v_permlane32_swap_b32_e32 v6, v8
	v_permlane32_swap_b32_e32 v7, v9
	v_mul_f32_e32 v14, v0, v48
	v_mul_f32_e32 v15, v0, v49
	v_mul_f32_e32 v48, v0, v50
	v_mul_f32_e32 v49, v0, v51
	v_mul_f32_e32 v50, v0, v52
	v_mul_f32_e32 v51, v0, v53
	v_mul_f32_e32 v52, v0, v54
	v_mul_f32_e32 v53, v0, v55
	global_store_dwordx4 v[4:5], v[6:9], off offset:2080
	s_waitcnt vmcnt(12)
	v_mov_b32_e32 v10, v84
	v_mov_b32_e32 v11, v85
	v_mov_b32_e32 v12, v86
	v_mov_b32_e32 v13, v87
	s_nop 0
	v_lshlrev_b32_e32 v6, 16, v10
	v_and_b32_e32 v7, 0xffff0000, v10
	v_lshlrev_b32_e32 v8, 16, v11
	v_and_b32_e32 v9, 0xffff0000, v11
	v_lshlrev_b32_e32 v10, 16, v12
	v_and_b32_e32 v11, 0xffff0000, v12
	v_lshlrev_b32_e32 v12, 16, v13
	v_and_b32_e32 v13, 0xffff0000, v13
	v_mul_f32_e32 v6, v14, v6
	v_mul_f32_e32 v7, v15, v7
	v_mul_f32_e32 v8, v48, v8
	v_mul_f32_e32 v9, v49, v9
	v_mul_f32_e32 v10, v50, v10
	v_mul_f32_e32 v11, v51, v11
	v_mul_f32_e32 v12, v52, v12
	v_mul_f32_e32 v13, v53, v13
	v_cvt_pk_bf16_f32 v6, v6, v7
	v_cvt_pk_bf16_f32 v7, v8, v9
	v_cvt_pk_bf16_f32 v8, v10, v11
	v_cvt_pk_bf16_f32 v9, v12, v13
	v_permlane32_swap_b32_e32 v6, v8
	v_permlane32_swap_b32_e32 v7, v9
	v_mul_f32_e32 v14, v0, v56
	v_mul_f32_e32 v15, v0, v57
	v_mul_f32_e32 v48, v0, v58
	v_mul_f32_e32 v49, v0, v59
	v_mul_f32_e32 v50, v0, v60
	v_mul_f32_e32 v51, v0, v61
	v_mul_f32_e32 v52, v0, v62
	v_mul_f32_e32 v53, v0, v63
	global_store_dwordx4 v[4:5], v[6:9], off offset:2112
	s_waitcnt vmcnt(11)
	v_mov_b32_e32 v10, v88
	v_mov_b32_e32 v11, v89
	v_mov_b32_e32 v12, v90
	v_mov_b32_e32 v13, v91
	s_nop 0
	v_lshlrev_b32_e32 v6, 16, v10
	v_and_b32_e32 v7, 0xffff0000, v10
	v_lshlrev_b32_e32 v8, 16, v11
	v_and_b32_e32 v9, 0xffff0000, v11
	v_lshlrev_b32_e32 v10, 16, v12
	v_and_b32_e32 v11, 0xffff0000, v12
	v_lshlrev_b32_e32 v12, 16, v13
	v_and_b32_e32 v13, 0xffff0000, v13
	v_mul_f32_e32 v6, v14, v6
	v_mul_f32_e32 v7, v15, v7
	v_mul_f32_e32 v8, v48, v8
	v_mul_f32_e32 v9, v49, v9
	v_mul_f32_e32 v10, v50, v10
	v_mul_f32_e32 v11, v51, v11
	v_mul_f32_e32 v12, v52, v12
	v_mul_f32_e32 v13, v53, v13
	v_cvt_pk_bf16_f32 v6, v6, v7
	v_cvt_pk_bf16_f32 v7, v8, v9
	v_cvt_pk_bf16_f32 v8, v10, v11
	v_cvt_pk_bf16_f32 v9, v12, v13
	v_permlane32_swap_b32_e32 v6, v8
	v_permlane32_swap_b32_e32 v7, v9
	v_mul_f32_e32 v14, v0, v32
	v_mul_f32_e32 v15, v0, v33
	v_mul_f32_e32 v32, v0, v34
	v_mul_f32_e32 v33, v0, v35
	v_mul_f32_e32 v34, v0, v36
	v_mul_f32_e32 v35, v0, v37
	v_mul_f32_e32 v36, v0, v38
	v_mul_f32_e32 v37, v0, v39
	global_store_dwordx4 v[4:5], v[6:9], off offset:2144
	s_waitcnt vmcnt(10)
	v_mov_b32_e32 v10, v92
	v_mov_b32_e32 v11, v93
	v_mov_b32_e32 v12, v94
	v_mov_b32_e32 v13, v95
	s_nop 0
	v_lshlrev_b32_e32 v6, 16, v10
	v_and_b32_e32 v7, 0xffff0000, v10
	v_lshlrev_b32_e32 v8, 16, v11
	v_and_b32_e32 v9, 0xffff0000, v11
	v_lshlrev_b32_e32 v10, 16, v12
	v_and_b32_e32 v11, 0xffff0000, v12
	v_lshlrev_b32_e32 v12, 16, v13
	v_and_b32_e32 v13, 0xffff0000, v13
	v_mul_f32_e32 v6, v14, v6
	v_mul_f32_e32 v7, v15, v7
	v_mul_f32_e32 v8, v32, v8
	v_mul_f32_e32 v9, v33, v9
	v_mul_f32_e32 v10, v34, v10
	v_mul_f32_e32 v11, v35, v11
	v_mul_f32_e32 v12, v36, v12
	v_mul_f32_e32 v13, v37, v13
	v_cvt_pk_bf16_f32 v6, v6, v7
	v_cvt_pk_bf16_f32 v7, v8, v9
	v_cvt_pk_bf16_f32 v8, v10, v11
	v_cvt_pk_bf16_f32 v9, v12, v13
	v_permlane32_swap_b32_e32 v6, v8
	v_permlane32_swap_b32_e32 v7, v9
	v_mul_f32_e32 v14, v0, v40
	v_mul_f32_e32 v15, v0, v41
	v_mul_f32_e32 v32, v0, v42
	v_mul_f32_e32 v33, v0, v43
	v_mul_f32_e32 v34, v0, v44
	v_mul_f32_e32 v35, v0, v45
	v_mul_f32_e32 v36, v0, v46
	v_mul_f32_e32 v37, v0, v47
	global_store_dwordx4 v[4:5], v[6:9], off offset:2176
	s_waitcnt vmcnt(9)
	v_mov_b32_e32 v10, v96
	v_mov_b32_e32 v11, v97
	v_mov_b32_e32 v12, v98
	v_mov_b32_e32 v13, v99
	s_nop 0
	v_lshlrev_b32_e32 v6, 16, v10
	v_and_b32_e32 v7, 0xffff0000, v10
	v_lshlrev_b32_e32 v8, 16, v11
	v_and_b32_e32 v9, 0xffff0000, v11
	v_lshlrev_b32_e32 v10, 16, v12
	v_and_b32_e32 v11, 0xffff0000, v12
	v_lshlrev_b32_e32 v12, 16, v13
	v_and_b32_e32 v13, 0xffff0000, v13
	v_mul_f32_e32 v6, v14, v6
	v_mul_f32_e32 v7, v15, v7
	v_mul_f32_e32 v8, v32, v8
	v_mul_f32_e32 v9, v33, v9
	v_mul_f32_e32 v10, v34, v10
	v_mul_f32_e32 v11, v35, v11
	v_mul_f32_e32 v12, v36, v12
	v_mul_f32_e32 v13, v37, v13
	v_cvt_pk_bf16_f32 v6, v6, v7
	v_cvt_pk_bf16_f32 v7, v8, v9
	v_cvt_pk_bf16_f32 v8, v10, v11
	v_cvt_pk_bf16_f32 v9, v12, v13
	v_permlane32_swap_b32_e32 v6, v8
	v_permlane32_swap_b32_e32 v7, v9
	v_mul_f32_e32 v14, v0, v16
	v_mul_f32_e32 v15, v0, v17
	v_mul_f32_e32 v16, v0, v18
	v_mul_f32_e32 v17, v0, v19
	v_mul_f32_e32 v18, v0, v20
	v_mul_f32_e32 v19, v0, v21
	global_store_dwordx4 v[4:5], v[6:9], off offset:2208
	v_mul_f32_e32 v20, v0, v22
	v_mul_f32_e32 v21, v0, v23
	s_waitcnt vmcnt(8)
	v_mov_b32_e32 v10, v100
	v_mov_b32_e32 v11, v101
	v_mov_b32_e32 v12, v102
	v_mov_b32_e32 v13, v103
	v_lshlrev_b32_e32 v6, 16, v10
	v_and_b32_e32 v7, 0xffff0000, v10
	v_lshlrev_b32_e32 v8, 16, v11
	v_and_b32_e32 v9, 0xffff0000, v11
	v_lshlrev_b32_e32 v10, 16, v12
	v_and_b32_e32 v11, 0xffff0000, v12
	v_lshlrev_b32_e32 v12, 16, v13
	v_and_b32_e32 v13, 0xffff0000, v13
	v_mul_f32_e32 v6, v14, v6
	v_mul_f32_e32 v7, v15, v7
	v_mul_f32_e32 v8, v16, v8
	v_mul_f32_e32 v9, v17, v9
	v_mul_f32_e32 v10, v18, v10
	v_mul_f32_e32 v11, v19, v11
	v_mul_f32_e32 v12, v20, v12
	v_mul_f32_e32 v13, v21, v13
	v_cvt_pk_bf16_f32 v6, v6, v7
	v_cvt_pk_bf16_f32 v7, v8, v9
	v_cvt_pk_bf16_f32 v8, v10, v11
	v_cvt_pk_bf16_f32 v9, v12, v13
	s_nop 0
	v_permlane32_swap_b32_e32 v6, v8
	v_permlane32_swap_b32_e32 v7, v9
	v_mul_f32_e32 v12, v0, v24
	v_mul_f32_e32 v13, v0, v25
	v_mul_f32_e32 v14, v0, v26
	v_mul_f32_e32 v15, v0, v27
	global_store_dwordx4 v[4:5], v[6:9], off offset:2240
	v_mul_f32_e32 v16, v0, v28
	v_mul_f32_e32 v17, v0, v29
	v_mul_f32_e32 v18, v0, v30
	v_mul_f32_e32 v0, v0, v31
	s_waitcnt vmcnt(7)
	v_mov_b32_e32 v10, v104
	v_mov_b32_e32 v11, v105
	v_mov_b32_e32 v2, v106
	v_mov_b32_e32 v3, v107
	v_lshlrev_b32_e32 v6, 16, v10
	v_and_b32_e32 v7, 0xffff0000, v10
	v_lshlrev_b32_e32 v8, 16, v11
	v_and_b32_e32 v9, 0xffff0000, v11
	v_lshlrev_b32_e32 v10, 16, v2
	v_and_b32_e32 v2, 0xffff0000, v2
	v_lshlrev_b32_e32 v11, 16, v3
	v_and_b32_e32 v3, 0xffff0000, v3
	v_mul_f32_e32 v6, v12, v6
	v_mul_f32_e32 v7, v13, v7
	v_mul_f32_e32 v8, v14, v8
	v_mul_f32_e32 v9, v15, v9
	v_mul_f32_e32 v10, v16, v10
	v_mul_f32_e32 v2, v17, v2
	v_mul_f32_e32 v11, v18, v11
	v_mul_f32_e32 v0, v0, v3
	v_cvt_pk_bf16_f32 v6, v6, v7
	v_cvt_pk_bf16_f32 v7, v8, v9
	v_cvt_pk_bf16_f32 v8, v10, v2
	v_cvt_pk_bf16_f32 v9, v11, v0
	s_nop 0
	v_permlane32_swap_b32_e32 v6, v8
	v_permlane32_swap_b32_e32 v7, v9
	global_store_dwordx4 v[4:5], v[6:9], off offset:2272
	s_waitcnt vmcnt(0) lgkmcnt(0)
	s_barrier
	s_cbranch_vccnz .LBB0_515
